# prep: x/p bf16 conversion stream fused into the weight-transpose tile loops (5 chunks per tile), tail loop finishes the rest
# speedup vs baseline: 1.0036x; 1.0036x over previous
; DI int otid() { int t = threadIdx.x; asm volatile("" : "+v"(t)); return t; }
; DI void prep_transpose(const float* W, int K, int Nsrc, int Nd, int kind, const float* kscale, bf16_t* dst, float* tileL, int L, int G) {
;   const int tid = otid();
;   const int ktiles = K / 64, ntiles = Nd / 64;
;   for (int t = L; t < ktiles * ntiles; t += G) {
;     const int nt = t / ktiles, kt = t - nt * ktiles;
;     const int k0 = kt * 64, n0 = nt * 64;
;     const int tx = tid & 63, ty = tid >> 6;
;     const int src = colmap(kind, n0 + tx);
;     __syncthreads();
; DI void phase_prep(const Params& P, unsigned char* smem, int L, int G) {
;     ...
;     bf16_t* xbw = (bf16_t*)(ws + OFF_XB); bf16_t* pbw = (bf16_t*)(ws + OFF_PB);
;     const size_t nx8 = (size_t)MTOK * 1024 / 8, np8 = (size_t)4 * MTOK * 256 / 8;
;     for (size_t idx = (size_t)L * NTHR + tid; idx < nx8 + np8; idx += (size_t)G * NTHR) {
.LBB0_22:
	v_lshl_add_u32 v236, s70, 9, v192
	v_readlane_b32 s98, v246, 1
	v_readlane_b32 s99, v246, 2
	v_readlane_b32 s100, v246, 3
	v_readlane_b32 s101, v246, 4
	s_nop 1
	v_mov_b32_e32 v238, s98
	v_mov_b32_e32 v239, s99
	v_mov_b32_e32 v240, s100
	v_mov_b32_e32 v241, s101
	v_mov_b32_e32 v242, 0x4f68800
	v_mov_b32_e32 v243, 0x3637c800
	s_cmpk_lt_i32 s70, 0x280
	v_mov_b32_e32 v0, v192
	v_mov_b32_e32 v2, v192
	s_cselect_b64 s[4:5], -1, 0
	s_cmpk_gt_i32 s70, 0x27f
	s_cbranch_scc1 .LBB0_30
	v_and_b32_e32 v1, 63, v2
	v_ashrrev_i32_e32 v8, 6, v2
	v_ashrrev_i32_e32 v9, 3, v2
	v_lshlrev_b32_e32 v2, 3, v2
	v_and_b32_e32 v2, 56, v2
	v_mul_u32_u24_e32 v4, 0x41, v2
	v_lshlrev_b32_e32 v4, 2, v4
	s_movk_i32 s2, 0x104
	v_mov_b32_e32 v3, 0
	v_lshl_add_u32 v10, v9, 2, v4
	v_mul_lo_u32 v4, v8, s2
	v_cmp_gt_i32_e64 s[0:1], 64, v8
	s_lshl_b32 s10, s70, 6
	s_lshl_b32 s11, s74, 6
	v_lshl_add_u32 v11, v1, 2, v4
	s_movk_i32 s28, 0x2800
	v_lshlrev_b32_e32 v4, 1, v2
	v_mov_b32_e32 v5, v3
	v_add_u32_e32 v12, 0x400, v10
	s_mov_b32 s29, s70
	s_branch .LBB0_25

; DI u32x4 cvt8(f32x4 a, f32x4 b) { u32x4 r; r.x = pack2(a.x, a.y); r.y = pack2(a.z, a.w); r.z = pack2(b.x, b.y); r.w = pack2(b.z, b.w); return r; }
; DI void phase_prep(const Params& P, unsigned char* smem, int L, int G) {
;     ...
;     bf16_t* xbw = (bf16_t*)(ws + OFF_XB); bf16_t* pbw = (bf16_t*)(ws + OFF_PB);
;     const size_t nx8 = (size_t)MTOK * 1024 / 8, np8 = (size_t)4 * MTOK * 256 / 8;
;     for (size_t idx = (size_t)L * NTHR + tid; idx < nx8 + np8; idx += (size_t)G * NTHR) {
;       const bool isx = idx < nx8;
;       const size_t e = (isx ? idx : idx - nx8) * 8;
;       const float* src = (isx ? P.x : P.p) + e;
;       const f32x4 f0 = ldgf4(src), f1 = ldgf4(src + 4);
;       *(u32x4*)((isx ? xbw : pbw) + e) = cvt8(f0, f1);
;     }
.LBB0_28:
	s_mov_b64 s[98:99], exec
	s_mov_b64 s[100:101], vcc
	s_mov_b64 exec, -1
	v_cmp_gt_u32_e32 vcc, 0x1000000, v236
	s_nop 1
	s_and_b64 exec, exec, vcc
	s_cbranch_execz .Lmy_cvA0
	v_mov_b32_e32 v227, 0
	v_mov_b32_e32 v228, v236
	v_mov_b32_e32 v224, v236
	v_cmp_gt_u32_e32 vcc, 0x800000, v224
	v_subrev_u32_e32 v226, 0x800000, v224
	v_mov_b32_e32 v179, 0
	v_cndmask_b32_e32 v226, v226, v224, vcc
	v_cndmask_b32_e32 v170, v240, v238, vcc
	v_cndmask_b32_e32 v171, v241, v239, vcc
	v_cndmask_b32_e32 v178, v243, v242, vcc
	v_lshlrev_b32_e32 v226, 3, v226
	v_lshl_add_u64 v[170:171], v[226:227], 2, v[170:171]
	v_lshl_add_u64 v[178:179], s[72:73], 0, v[178:179]
	v_lshl_add_u64 v[178:179], v[226:227], 1, v[178:179]
	v_mov_b32_e32 v174, v170
	v_mov_b32_e32 v175, v171
	global_load_dwordx4 v[170:173], v[170:171], off
	global_load_dwordx4 v[174:177], v[174:175], off offset:16
	v_lshl_add_u32 v228, s74, 9, v228
	v_cmp_gt_u32_e32 vcc, 0x1000000, v228
	v_mov_b32_e32 v224, v228
	s_nop 0
	v_cndmask_b32_e32 v224, v236, v224, vcc
	v_cmp_gt_u32_e32 vcc, 0x800000, v224
	v_subrev_u32_e32 v226, 0x800000, v224
	v_mov_b32_e32 v189, 0
	v_cndmask_b32_e32 v226, v226, v224, vcc
	v_cndmask_b32_e32 v180, v240, v238, vcc
	v_cndmask_b32_e32 v181, v241, v239, vcc
	v_cndmask_b32_e32 v188, v243, v242, vcc
	v_lshlrev_b32_e32 v226, 3, v226
	v_lshl_add_u64 v[180:181], v[226:227], 2, v[180:181]
	v_lshl_add_u64 v[188:189], s[72:73], 0, v[188:189]
	v_lshl_add_u64 v[188:189], v[226:227], 1, v[188:189]
	v_mov_b32_e32 v184, v180
	v_mov_b32_e32 v185, v181
	global_load_dwordx4 v[180:183], v[180:181], off
	global_load_dwordx4 v[184:187], v[184:185], off offset:16
	v_lshl_add_u32 v228, s74, 9, v228
	v_cmp_gt_u32_e32 vcc, 0x1000000, v228
	v_mov_b32_e32 v224, v228
	s_nop 0
	v_cndmask_b32_e32 v224, v236, v224, vcc
	v_cmp_gt_u32_e32 vcc, 0x800000, v224
	v_subrev_u32_e32 v226, 0x800000, v224
	v_mov_b32_e32 v203, 0
	v_cndmask_b32_e32 v226, v226, v224, vcc
	v_cndmask_b32_e32 v194, v240, v238, vcc
	v_cndmask_b32_e32 v195, v241, v239, vcc
	v_cndmask_b32_e32 v202, v243, v242, vcc
	v_lshlrev_b32_e32 v226, 3, v226
	v_lshl_add_u64 v[194:195], v[226:227], 2, v[194:195]
	v_lshl_add_u64 v[202:203], s[72:73], 0, v[202:203]
	v_lshl_add_u64 v[202:203], v[226:227], 1, v[202:203]
	v_mov_b32_e32 v198, v194
	v_mov_b32_e32 v199, v195
	global_load_dwordx4 v[194:197], v[194:195], off
	global_load_dwordx4 v[198:201], v[198:199], off offset:16
	v_lshl_add_u32 v228, s74, 9, v228
	v_cmp_gt_u32_e32 vcc, 0x1000000, v228
	v_mov_b32_e32 v224, v228
	s_nop 0
	v_cndmask_b32_e32 v224, v236, v224, vcc
	v_cmp_gt_u32_e32 vcc, 0x800000, v224
	v_subrev_u32_e32 v226, 0x800000, v224
	v_mov_b32_e32 v213, 0
	v_cndmask_b32_e32 v226, v226, v224, vcc
	v_cndmask_b32_e32 v204, v240, v238, vcc
	v_cndmask_b32_e32 v205, v241, v239, vcc
	v_cndmask_b32_e32 v212, v243, v242, vcc
	v_lshlrev_b32_e32 v226, 3, v226
	v_lshl_add_u64 v[204:205], v[226:227], 2, v[204:205]
	v_lshl_add_u64 v[212:213], s[72:73], 0, v[212:213]
	v_lshl_add_u64 v[212:213], v[226:227], 1, v[212:213]
	v_mov_b32_e32 v208, v204
	v_mov_b32_e32 v209, v205
	global_load_dwordx4 v[204:207], v[204:205], off
	global_load_dwordx4 v[208:211], v[208:209], off offset:16
	v_lshl_add_u32 v228, s74, 9, v228
	v_cmp_gt_u32_e32 vcc, 0x1000000, v228
	v_mov_b32_e32 v224, v228
	s_nop 0
	v_cndmask_b32_e32 v224, v236, v224, vcc
	v_cmp_gt_u32_e32 vcc, 0x800000, v224
	v_subrev_u32_e32 v226, 0x800000, v224
	v_mov_b32_e32 v223, 0
	v_cndmask_b32_e32 v226, v226, v224, vcc
	v_cndmask_b32_e32 v214, v240, v238, vcc
	v_cndmask_b32_e32 v215, v241, v239, vcc
	v_cndmask_b32_e32 v222, v243, v242, vcc
	v_lshlrev_b32_e32 v226, 3, v226
	v_lshl_add_u64 v[214:215], v[226:227], 2, v[214:215]
	v_lshl_add_u64 v[222:223], s[72:73], 0, v[222:223]
	v_lshl_add_u64 v[222:223], v[226:227], 1, v[222:223]
	v_mov_b32_e32 v218, v214
	v_mov_b32_e32 v219, v215
	global_load_dwordx4 v[214:217], v[214:215], off
	global_load_dwordx4 v[218:221], v[218:219], off offset:16
; DI u32x4 cvt8(f32x4 a, f32x4 b) { u32x4 r; r.x = pack2(a.x, a.y); r.y = pack2(a.z, a.w); r.z = pack2(b.x, b.y); r.w = pack2(b.z, b.w); return r; }
; DI void prep_transpose(const float* W, int K, int Nsrc, int Nd, int kind, const float* kscale, bf16_t* dst, float* tileL, int L, int G) {
;     ...
;     __syncthreads();
;     for (int kk = ty; kk < 64; kk += 8) {
;       float v = 0.f;
;       if (src >= 0) { v = W[(size_t)(k0 + kk) * Nsrc + src]; if (kscale) v *= kscale[k0 + kk]; }
;       tileL[kk * 65 + tx] = v;
;     }
;     __syncthreads();
; DI void phase_prep(const Params& P, unsigned char* smem, int L, int G) {
;     ...
;     for (size_t idx = (size_t)L * NTHR + tid; idx < nx8 + np8; idx += (size_t)G * NTHR) {
;       const bool isx = idx < nx8;
;       const size_t e = (isx ? idx : idx - nx8) * 8;
;       const float* src = (isx ? P.x : P.p) + e;
;       const f32x4 f0 = ldgf4(src), f1 = ldgf4(src + 4);
;       *(u32x4*)((isx ? xbw : pbw) + e) = cvt8(f0, f1);
;     }
.Lmy_cvA0:
	s_mov_b64 exec, s[98:99]
	s_mov_b64 vcc, s[100:101]
	v_mov_b32_e32 v40, 0
	v_mov_b32_e32 v56, 0
	v_mov_b32_e32 v72, 0
	v_mov_b32_e32 v88, 0
	v_mov_b32_e32 v104, 0
	v_mov_b32_e32 v120, 0
	v_mov_b32_e32 v136, 0
	v_mov_b32_e32 v152, 0
	s_and_b64 vcc, exec, s[2:3]
	s_cbranch_vccnz .Lmy_tp0_w
	v_add_u32_e32 v40, s33, v13
	v_mad_i64_i32 v[40:41], s[34:35], v40, s28, v[6:7]
	global_load_dword v40, v[40:41], off
	v_add_u32_e32 v71, 8, v13
	v_add_u32_e32 v56, s33, v71
	v_mad_i64_i32 v[56:57], s[34:35], v56, s28, v[6:7]
	global_load_dword v56, v[56:57], off
	v_add_u32_e32 v87, 16, v13
	v_add_u32_e32 v72, s33, v87
	v_mad_i64_i32 v[72:73], s[34:35], v72, s28, v[6:7]
	global_load_dword v72, v[72:73], off
	v_add_u32_e32 v103, 24, v13
	v_add_u32_e32 v88, s33, v103
	v_mad_i64_i32 v[88:89], s[34:35], v88, s28, v[6:7]
	global_load_dword v88, v[88:89], off
	v_add_u32_e32 v119, 32, v13
	v_add_u32_e32 v104, s33, v119
	v_mad_i64_i32 v[104:105], s[34:35], v104, s28, v[6:7]
	global_load_dword v104, v[104:105], off
	v_add_u32_e32 v135, 40, v13
	v_add_u32_e32 v120, s33, v135
	v_mad_i64_i32 v[120:121], s[34:35], v120, s28, v[6:7]
	global_load_dword v120, v[120:121], off
	v_add_u32_e32 v151, 48, v13
	v_add_u32_e32 v136, s33, v151
	v_mad_i64_i32 v[136:137], s[34:35], v136, s28, v[6:7]
	global_load_dword v136, v[136:137], off
	v_add_u32_e32 v167, 56, v13
	v_add_u32_e32 v152, s33, v167
	v_mad_i64_i32 v[152:153], s[34:35], v152, s28, v[6:7]
	global_load_dword v152, v[152:153], off
.Lmy_tp0_r:
.Lmy_tp0_w:
	s_waitcnt vmcnt(7)
	ds_write_b32 v2, v40
	s_waitcnt vmcnt(6)
	ds_write_b32 v2, v56 offset:2080
	s_waitcnt vmcnt(5)
	ds_write_b32 v2, v72 offset:4160
	s_waitcnt vmcnt(4)
	ds_write_b32 v2, v88 offset:6240
	s_waitcnt vmcnt(3)
	ds_write_b32 v2, v104 offset:8320
	s_waitcnt vmcnt(2)
	ds_write_b32 v2, v120 offset:10400
	s_waitcnt vmcnt(1)
	ds_write_b32 v2, v136 offset:12480
	s_waitcnt vmcnt(0)
	ds_write_b32 v2, v152 offset:14560
	s_mov_b64 s[98:99], exec
	s_mov_b64 s[100:101], vcc
	s_mov_b64 exec, -1
	v_cmp_gt_u32_e32 vcc, 0x1000000, v236
	s_nop 1
	s_and_b64 exec, exec, vcc
	s_cbranch_execz .Lmy_cvB0
	s_waitcnt vmcnt(0)
	v_cvt_pk_bf16_f32 v170, v170, v171
	v_cvt_pk_bf16_f32 v171, v172, v173
	v_cvt_pk_bf16_f32 v172, v174, v175
	v_cvt_pk_bf16_f32 v173, v176, v177
	global_store_dwordx4 v[178:179], v[170:173], off
	v_cvt_pk_bf16_f32 v180, v180, v181
	v_cvt_pk_bf16_f32 v181, v182, v183
	v_cvt_pk_bf16_f32 v182, v184, v185
	v_cvt_pk_bf16_f32 v183, v186, v187
	global_store_dwordx4 v[188:189], v[180:183], off
	v_cvt_pk_bf16_f32 v194, v194, v195
	v_cvt_pk_bf16_f32 v195, v196, v197
	v_cvt_pk_bf16_f32 v196, v198, v199
	v_cvt_pk_bf16_f32 v197, v200, v201
	global_store_dwordx4 v[202:203], v[194:197], off
	v_cvt_pk_bf16_f32 v204, v204, v205
	v_cvt_pk_bf16_f32 v205, v206, v207
	v_cvt_pk_bf16_f32 v206, v208, v209
	v_cvt_pk_bf16_f32 v207, v210, v211
	global_store_dwordx4 v[212:213], v[204:207], off
	v_cvt_pk_bf16_f32 v214, v214, v215
	v_cvt_pk_bf16_f32 v215, v216, v217
	v_cvt_pk_bf16_f32 v216, v218, v219
	v_cvt_pk_bf16_f32 v217, v220, v221
	global_store_dwordx4 v[222:223], v[214:217], off
	v_lshl_add_u32 v236, s74, 9, v228
.Lmy_cvB0:
	s_mov_b64 exec, s[98:99]
	s_mov_b64 vcc, s[100:101]
	s_branch .LBB0_24

; DI void prep_transpose(const float* W, int K, int Nsrc, int Nd, int kind, const float* kscale, bf16_t* dst, float* tileL, int L, int G) {
;     ...
;     __syncthreads();
;     for (int kk = ty; kk < 64; kk += 8) {
;       float v = 0.f;
;       if (src >= 0) { v = W[(size_t)(k0 + kk) * Nsrc + src]; if (kscale) v *= kscale[k0 + kk]; }
;       tileL[kk * 65 + tx] = v;
.Lmy_cvA1:
	s_mov_b64 exec, s[98:99]
	s_mov_b64 vcc, s[100:101]
	v_mov_b32_e32 v40, 0
	v_mov_b32_e32 v56, 0
	v_mov_b32_e32 v72, 0
	v_mov_b32_e32 v88, 0
	v_mov_b32_e32 v104, 0
	v_mov_b32_e32 v120, 0
	v_mov_b32_e32 v136, 0
	v_mov_b32_e32 v152, 0
	s_and_saveexec_b64 s[2:3], vcc
	s_cbranch_execz .Lmy_tp1_r
	v_add_u32_e32 v40, s35, v13
	v_mad_i64_i32 v[40:41], s[36:37], v40, s30, v[6:7]
	global_load_dword v40, v[40:41], off
	v_add_u32_e32 v71, 8, v13
	v_add_u32_e32 v56, s35, v71
	v_mad_i64_i32 v[56:57], s[36:37], v56, s30, v[6:7]
	global_load_dword v56, v[56:57], off
	v_add_u32_e32 v87, 16, v13
	v_add_u32_e32 v72, s35, v87
	v_mad_i64_i32 v[72:73], s[36:37], v72, s30, v[6:7]
	global_load_dword v72, v[72:73], off
	v_add_u32_e32 v103, 24, v13
	v_add_u32_e32 v88, s35, v103
	v_mad_i64_i32 v[88:89], s[36:37], v88, s30, v[6:7]
	global_load_dword v88, v[88:89], off
	v_add_u32_e32 v119, 32, v13
	v_add_u32_e32 v104, s35, v119
	v_mad_i64_i32 v[104:105], s[36:37], v104, s30, v[6:7]
	global_load_dword v104, v[104:105], off
	v_add_u32_e32 v135, 40, v13
	v_add_u32_e32 v120, s35, v135
	v_mad_i64_i32 v[120:121], s[36:37], v120, s30, v[6:7]
	global_load_dword v120, v[120:121], off
	v_add_u32_e32 v151, 48, v13
	v_add_u32_e32 v136, s35, v151
	v_mad_i64_i32 v[136:137], s[36:37], v136, s30, v[6:7]
	global_load_dword v136, v[136:137], off
	v_add_u32_e32 v167, 56, v13
	v_add_u32_e32 v152, s35, v167
	v_mad_i64_i32 v[152:153], s[36:37], v152, s30, v[6:7]
	global_load_dword v152, v[152:153], off

; DI u32x4 cvt8(f32x4 a, f32x4 b) { u32x4 r; r.x = pack2(a.x, a.y); r.y = pack2(a.z, a.w); r.z = pack2(b.x, b.y); r.w = pack2(b.z, b.w); return r; }
; DI void prep_transpose(const float* W, int K, int Nsrc, int Nd, int kind, const float* kscale, bf16_t* dst, float* tileL, int L, int G) {
;     ...
;       tileL[kk * 65 + tx] = v;
;     }
;     __syncthreads();
; DI void phase_prep(const Params& P, unsigned char* smem, int L, int G) {
;     ...
;     for (size_t idx = (size_t)L * NTHR + tid; idx < nx8 + np8; idx += (size_t)G * NTHR) {
;       const bool isx = idx < nx8;
;       const size_t e = (isx ? idx : idx - nx8) * 8;
;       const float* src = (isx ? P.x : P.p) + e;
;       const f32x4 f0 = ldgf4(src), f1 = ldgf4(src + 4);
;       *(u32x4*)((isx ? xbw : pbw) + e) = cvt8(f0, f1);
;     }
.Lmy_tp1_w:
	s_waitcnt vmcnt(7)
	ds_write_b32 v2, v40
	s_waitcnt vmcnt(6)
	ds_write_b32 v2, v56 offset:2080
	s_waitcnt vmcnt(5)
	ds_write_b32 v2, v72 offset:4160
	s_waitcnt vmcnt(4)
	ds_write_b32 v2, v88 offset:6240
	s_waitcnt vmcnt(3)
	ds_write_b32 v2, v104 offset:8320
	s_waitcnt vmcnt(2)
	ds_write_b32 v2, v120 offset:10400
	s_waitcnt vmcnt(1)
	ds_write_b32 v2, v136 offset:12480
	s_waitcnt vmcnt(0)
	ds_write_b32 v2, v152 offset:14560
	s_mov_b64 s[98:99], exec
	s_mov_b64 s[100:101], vcc
	s_mov_b64 exec, -1
	v_cmp_gt_u32_e32 vcc, 0x1000000, v236
	s_nop 1
	s_and_b64 exec, exec, vcc
	s_cbranch_execz .Lmy_cvB1
	s_waitcnt vmcnt(0)
	v_cvt_pk_bf16_f32 v170, v170, v171
	v_cvt_pk_bf16_f32 v171, v172, v173
	v_cvt_pk_bf16_f32 v172, v174, v175
	v_cvt_pk_bf16_f32 v173, v176, v177
	global_store_dwordx4 v[178:179], v[170:173], off
	v_cvt_pk_bf16_f32 v180, v180, v181
	v_cvt_pk_bf16_f32 v181, v182, v183
	v_cvt_pk_bf16_f32 v182, v184, v185
	v_cvt_pk_bf16_f32 v183, v186, v187
	global_store_dwordx4 v[188:189], v[180:183], off
	v_cvt_pk_bf16_f32 v194, v194, v195
	v_cvt_pk_bf16_f32 v195, v196, v197
	v_cvt_pk_bf16_f32 v196, v198, v199
	v_cvt_pk_bf16_f32 v197, v200, v201
	global_store_dwordx4 v[202:203], v[194:197], off
	v_cvt_pk_bf16_f32 v204, v204, v205
	v_cvt_pk_bf16_f32 v205, v206, v207
	v_cvt_pk_bf16_f32 v206, v208, v209
	v_cvt_pk_bf16_f32 v207, v210, v211
	global_store_dwordx4 v[212:213], v[204:207], off
	v_cvt_pk_bf16_f32 v214, v214, v215
	v_cvt_pk_bf16_f32 v215, v216, v217
	v_cvt_pk_bf16_f32 v216, v218, v219
	v_cvt_pk_bf16_f32 v217, v220, v221
	global_store_dwordx4 v[222:223], v[214:217], off
	v_lshl_add_u32 v236, s74, 9, v228

; DI void prep_transpose(const float* W, int K, int Nsrc, int Nd, int kind, const float* kscale, bf16_t* dst, float* tileL, int L, int G) {
;     ...
;     __syncthreads();
;     for (int kk = ty; kk < 64; kk += 8) {
;       float v = 0.f;
;       if (src >= 0) { v = W[(size_t)(k0 + kk) * Nsrc + src]; if (kscale) v *= kscale[k0 + kk]; }
;       tileL[kk * 65 + tx] = v;
.Lmy_cvA3:
	s_mov_b64 exec, s[98:99]
	s_mov_b64 vcc, s[100:101]
	v_mov_b32_e32 v40, 0
	v_mov_b32_e32 v56, 0
	v_mov_b32_e32 v72, 0
	v_mov_b32_e32 v88, 0
	v_mov_b32_e32 v104, 0
	v_mov_b32_e32 v120, 0
	v_mov_b32_e32 v136, 0
	v_mov_b32_e32 v152, 0
	s_and_b64 vcc, exec, s[2:3]
	s_cbranch_vccnz .Lmy_tp3_w
	v_add_u32_e32 v40, s26, v13
	v_mad_i64_i32 v[40:41], s[30:31], v40, s10, v[6:7]
	global_load_dword v40, v[40:41], off
	v_add_u32_e32 v71, 8, v13
	v_add_u32_e32 v56, s26, v71
	v_mad_i64_i32 v[56:57], s[30:31], v56, s10, v[6:7]
	global_load_dword v56, v[56:57], off
	v_add_u32_e32 v87, 16, v13
	v_add_u32_e32 v72, s26, v87
	v_mad_i64_i32 v[72:73], s[30:31], v72, s10, v[6:7]
	global_load_dword v72, v[72:73], off
	v_add_u32_e32 v103, 24, v13
	v_add_u32_e32 v88, s26, v103
	v_mad_i64_i32 v[88:89], s[30:31], v88, s10, v[6:7]
	global_load_dword v88, v[88:89], off
	v_add_u32_e32 v119, 32, v13
	v_add_u32_e32 v104, s26, v119
	v_mad_i64_i32 v[104:105], s[30:31], v104, s10, v[6:7]
	global_load_dword v104, v[104:105], off
	v_add_u32_e32 v135, 40, v13
	v_add_u32_e32 v120, s26, v135
	v_mad_i64_i32 v[120:121], s[30:31], v120, s10, v[6:7]
	global_load_dword v120, v[120:121], off
	v_add_u32_e32 v151, 48, v13
	v_add_u32_e32 v136, s26, v151
	v_mad_i64_i32 v[136:137], s[30:31], v136, s10, v[6:7]
	global_load_dword v136, v[136:137], off
	v_add_u32_e32 v167, 56, v13
	v_add_u32_e32 v152, s26, v167
	v_mad_i64_i32 v[152:153], s[30:31], v152, s10, v[6:7]
	global_load_dword v152, v[152:153], off

; DI void prep_transpose(const float* W, int K, int Nsrc, int Nd, int kind, const float* kscale, bf16_t* dst, float* tileL, int L, int G) {
;     ...
;     __syncthreads();
;     for (int kk = ty; kk < 64; kk += 8) {
;       float v = 0.f;
;       if (src >= 0) { v = W[(size_t)(k0 + kk) * Nsrc + src]; if (kscale) v *= kscale[k0 + kk]; }
;       tileL[kk * 65 + tx] = v;
.Lmy_cvA4:
	s_mov_b64 exec, s[98:99]
	s_mov_b64 vcc, s[100:101]
	v_mov_b32_e32 v48, 0
	v_mov_b32_e32 v64, 0
	v_mov_b32_e32 v80, 0
	v_mov_b32_e32 v96, 0
	v_mov_b32_e32 v112, 0
	v_mov_b32_e32 v128, 0
	v_mov_b32_e32 v144, 0
	v_mov_b32_e32 v160, 0
	s_and_saveexec_b64 s[10:11], s[4:5]
	s_cbranch_execz .Lmy_tp4_r
	v_add_u32_e32 v40, s38, v17
	v_mad_i64_i32 v[48:49], s[40:41], v40, s33, v[8:9]
	global_load_dword v48, v[48:49], off
	v_add_u32_e32 v71, 8, v17
	v_add_u32_e32 v56, s38, v71
	v_mad_i64_i32 v[64:65], s[40:41], v56, s33, v[8:9]
	global_load_dword v64, v[64:65], off
	v_add_u32_e32 v87, 16, v17
	v_add_u32_e32 v72, s38, v87
	v_mad_i64_i32 v[80:81], s[40:41], v72, s33, v[8:9]
	global_load_dword v80, v[80:81], off
	v_add_u32_e32 v103, 24, v17
	v_add_u32_e32 v88, s38, v103
	v_mad_i64_i32 v[96:97], s[40:41], v88, s33, v[8:9]
	global_load_dword v96, v[96:97], off
	v_add_u32_e32 v119, 32, v17
	v_add_u32_e32 v104, s38, v119
	v_mad_i64_i32 v[112:113], s[40:41], v104, s33, v[8:9]
	global_load_dword v112, v[112:113], off
	v_add_u32_e32 v135, 40, v17
	v_add_u32_e32 v120, s38, v135
	v_mad_i64_i32 v[128:129], s[40:41], v120, s33, v[8:9]
	global_load_dword v128, v[128:129], off
	v_add_u32_e32 v151, 48, v17
	v_add_u32_e32 v136, s38, v151
	v_mad_i64_i32 v[144:145], s[40:41], v136, s33, v[8:9]
	global_load_dword v144, v[144:145], off
	v_add_u32_e32 v167, 56, v17
	v_add_u32_e32 v152, s38, v167
	v_mad_i64_i32 v[160:161], s[40:41], v152, s33, v[8:9]
	global_load_dword v160, v[160:161], off
	s_and_b64 vcc, exec, s[2:3]
	s_cbranch_vccnz .Lmy_tp4_r
	v_ashrrev_i32_e32 v41, 31, v40
	v_lshl_add_u64 v[40:41], v[40:41], 2, s[18:19]
	global_load_dword v40, v[40:41], off
	v_ashrrev_i32_e32 v57, 31, v56
	v_lshl_add_u64 v[56:57], v[56:57], 2, s[18:19]
	global_load_dword v56, v[56:57], off
	v_ashrrev_i32_e32 v73, 31, v72
	v_lshl_add_u64 v[72:73], v[72:73], 2, s[18:19]
	global_load_dword v72, v[72:73], off
	v_ashrrev_i32_e32 v89, 31, v88
	v_lshl_add_u64 v[88:89], v[88:89], 2, s[18:19]
	global_load_dword v88, v[88:89], off
	v_ashrrev_i32_e32 v105, 31, v104
	v_lshl_add_u64 v[104:105], v[104:105], 2, s[18:19]
	global_load_dword v104, v[104:105], off
	v_ashrrev_i32_e32 v121, 31, v120
	v_lshl_add_u64 v[120:121], v[120:121], 2, s[18:19]
	global_load_dword v120, v[120:121], off
	v_ashrrev_i32_e32 v137, 31, v136
	v_lshl_add_u64 v[136:137], v[136:137], 2, s[18:19]
	global_load_dword v136, v[136:137], off
	v_ashrrev_i32_e32 v153, 31, v152
	v_lshl_add_u64 v[152:153], v[152:153], 2, s[18:19]
	global_load_dword v152, v[152:153], off
	s_waitcnt vmcnt(7)
	v_mul_f32_e32 v48, v48, v40
	s_waitcnt vmcnt(6)
	v_mul_f32_e32 v64, v64, v56
	s_waitcnt vmcnt(5)
	v_mul_f32_e32 v80, v80, v72
	s_waitcnt vmcnt(4)
	v_mul_f32_e32 v96, v96, v88
	s_waitcnt vmcnt(3)
	v_mul_f32_e32 v112, v112, v104
	s_waitcnt vmcnt(2)
	v_mul_f32_e32 v128, v128, v120
	s_waitcnt vmcnt(1)
	v_mul_f32_e32 v144, v144, v136
	s_waitcnt vmcnt(0)
	v_mul_f32_e32 v160, v160, v152

; DI u32x4 cvt8(f32x4 a, f32x4 b) { u32x4 r; r.x = pack2(a.x, a.y); r.y = pack2(a.z, a.w); r.z = pack2(b.x, b.y); r.w = pack2(b.z, b.w); return r; }
; DI void prep_transpose(const float* W, int K, int Nsrc, int Nd, int kind, const float* kscale, bf16_t* dst, float* tileL, int L, int G) {
;     ...
;       tileL[kk * 65 + tx] = v;
;     }
;     __syncthreads();
; DI void phase_prep(const Params& P, unsigned char* smem, int L, int G) {
;     ...
;     for (size_t idx = (size_t)L * NTHR + tid; idx < nx8 + np8; idx += (size_t)G * NTHR) {
;       const bool isx = idx < nx8;
;       const size_t e = (isx ? idx : idx - nx8) * 8;
;       const float* src = (isx ? P.x : P.p) + e;
;       const f32x4 f0 = ldgf4(src), f1 = ldgf4(src + 4);
;       *(u32x4*)((isx ? xbw : pbw) + e) = cvt8(f0, f1);
;     }
.Lmy_tp4_w:
	s_waitcnt vmcnt(7)
	ds_write_b32 v16, v48
	s_waitcnt vmcnt(6)
	ds_write_b32 v16, v64 offset:2080
	s_waitcnt vmcnt(5)
	ds_write_b32 v16, v80 offset:4160
	s_waitcnt vmcnt(4)
	ds_write_b32 v16, v96 offset:6240
	s_waitcnt vmcnt(3)
	ds_write_b32 v16, v112 offset:8320
	s_waitcnt vmcnt(2)
	ds_write_b32 v16, v128 offset:10400
	s_waitcnt vmcnt(1)
	ds_write_b32 v16, v144 offset:12480
	s_waitcnt vmcnt(0)
	ds_write_b32 v16, v160 offset:14560
	s_mov_b64 s[98:99], exec
	s_mov_b64 s[100:101], vcc
	s_mov_b64 exec, -1
	v_cmp_gt_u32_e32 vcc, 0x1000000, v236
	s_nop 1
	s_and_b64 exec, exec, vcc
	s_cbranch_execz .Lmy_cvB4
	s_waitcnt vmcnt(0)
	v_cvt_pk_bf16_f32 v170, v170, v171
	v_cvt_pk_bf16_f32 v171, v172, v173
	v_cvt_pk_bf16_f32 v172, v174, v175
	v_cvt_pk_bf16_f32 v173, v176, v177
	global_store_dwordx4 v[178:179], v[170:173], off
	v_cvt_pk_bf16_f32 v180, v180, v181
	v_cvt_pk_bf16_f32 v181, v182, v183
	v_cvt_pk_bf16_f32 v182, v184, v185
	v_cvt_pk_bf16_f32 v183, v186, v187
	global_store_dwordx4 v[188:189], v[180:183], off
	v_cvt_pk_bf16_f32 v194, v194, v195
	v_cvt_pk_bf16_f32 v195, v196, v197
	v_cvt_pk_bf16_f32 v196, v198, v199
	v_cvt_pk_bf16_f32 v197, v200, v201
	global_store_dwordx4 v[202:203], v[194:197], off
	v_cvt_pk_bf16_f32 v204, v204, v205
	v_cvt_pk_bf16_f32 v205, v206, v207
	v_cvt_pk_bf16_f32 v206, v208, v209
	v_cvt_pk_bf16_f32 v207, v210, v211
	global_store_dwordx4 v[212:213], v[204:207], off
	v_cvt_pk_bf16_f32 v214, v214, v215
	v_cvt_pk_bf16_f32 v215, v216, v217
	v_cvt_pk_bf16_f32 v216, v218, v219
	v_cvt_pk_bf16_f32 v217, v220, v221
	global_store_dwordx4 v[222:223], v[214:217], off
	v_lshl_add_u32 v236, s74, 9, v228

; DI void prep_transpose(const float* W, int K, int Nsrc, int Nd, int kind, const float* kscale, bf16_t* dst, float* tileL, int L, int G) {
;     ...
;     __syncthreads();
;     for (int kk = ty; kk < 64; kk += 8) {
;       float v = 0.f;
;       if (src >= 0) { v = W[(size_t)(k0 + kk) * Nsrc + src]; if (kscale) v *= kscale[k0 + kk]; }
;       tileL[kk * 65 + tx] = v;
.Lmy_cvA5:
	s_mov_b64 exec, s[98:99]
	s_mov_b64 vcc, s[100:101]
	v_mov_b32_e32 v49, 0
	v_mov_b32_e32 v65, 0
	v_mov_b32_e32 v81, 0
	v_mov_b32_e32 v97, 0
	v_mov_b32_e32 v113, 0
	v_mov_b32_e32 v129, 0
	v_mov_b32_e32 v145, 0
	v_mov_b32_e32 v161, 0
	s_and_saveexec_b64 s[12:13], s[4:5]
	s_cbranch_execz .Lmy_tp5_r
	v_add_u32_e32 v40, s37, v16
	v_ashrrev_i32_e32 v41, 31, v40
	v_lshlrev_b64 v[50:51], 13, v[40:41]
	v_lshl_add_u64 v[50:51], v[6:7], 0, v[50:51]
	global_load_dword v49, v[50:51], off
	v_add_u32_e32 v71, 8, v16
	v_add_u32_e32 v56, s37, v71
	v_ashrrev_i32_e32 v57, 31, v56
	v_lshlrev_b64 v[66:67], 13, v[56:57]
	v_lshl_add_u64 v[66:67], v[6:7], 0, v[66:67]
	global_load_dword v65, v[66:67], off
	v_add_u32_e32 v87, 16, v16
	v_add_u32_e32 v72, s37, v87
	v_ashrrev_i32_e32 v73, 31, v72
	v_lshlrev_b64 v[82:83], 13, v[72:73]
	v_lshl_add_u64 v[82:83], v[6:7], 0, v[82:83]
	global_load_dword v81, v[82:83], off
	v_add_u32_e32 v103, 24, v16
	v_add_u32_e32 v88, s37, v103
	v_ashrrev_i32_e32 v89, 31, v88
	v_lshlrev_b64 v[98:99], 13, v[88:89]
	v_lshl_add_u64 v[98:99], v[6:7], 0, v[98:99]
	global_load_dword v97, v[98:99], off
	v_add_u32_e32 v119, 32, v16
	v_add_u32_e32 v104, s37, v119
	v_ashrrev_i32_e32 v105, 31, v104
	v_lshlrev_b64 v[114:115], 13, v[104:105]
	v_lshl_add_u64 v[114:115], v[6:7], 0, v[114:115]
	global_load_dword v113, v[114:115], off
	v_add_u32_e32 v135, 40, v16
	v_add_u32_e32 v120, s37, v135
	v_ashrrev_i32_e32 v121, 31, v120
	v_lshlrev_b64 v[130:131], 13, v[120:121]
	v_lshl_add_u64 v[130:131], v[6:7], 0, v[130:131]
	global_load_dword v129, v[130:131], off
	v_add_u32_e32 v151, 48, v16
	v_add_u32_e32 v136, s37, v151
	v_ashrrev_i32_e32 v137, 31, v136
	v_lshlrev_b64 v[146:147], 13, v[136:137]
	v_lshl_add_u64 v[146:147], v[6:7], 0, v[146:147]
	global_load_dword v145, v[146:147], off
	v_add_u32_e32 v167, 56, v16
	v_add_u32_e32 v152, s37, v167
	v_ashrrev_i32_e32 v153, 31, v152
	v_lshlrev_b64 v[162:163], 13, v[152:153]
	v_lshl_add_u64 v[162:163], v[6:7], 0, v[162:163]
	global_load_dword v161, v[162:163], off
	s_and_b64 vcc, exec, s[2:3]
	s_cbranch_vccnz .Lmy_tp5_r
	v_lshl_add_u64 v[40:41], v[40:41], 2, s[20:21]
	global_load_dword v40, v[40:41], off
	v_lshl_add_u64 v[56:57], v[56:57], 2, s[20:21]
	global_load_dword v56, v[56:57], off
	v_lshl_add_u64 v[72:73], v[72:73], 2, s[20:21]
	global_load_dword v72, v[72:73], off
	v_lshl_add_u64 v[88:89], v[88:89], 2, s[20:21]
	global_load_dword v88, v[88:89], off
	v_lshl_add_u64 v[104:105], v[104:105], 2, s[20:21]
	global_load_dword v104, v[104:105], off
	v_lshl_add_u64 v[120:121], v[120:121], 2, s[20:21]
	global_load_dword v120, v[120:121], off
	v_lshl_add_u64 v[136:137], v[136:137], 2, s[20:21]
	global_load_dword v136, v[136:137], off
	v_lshl_add_u64 v[152:153], v[152:153], 2, s[20:21]
	global_load_dword v152, v[152:153], off
	s_waitcnt vmcnt(7)
	v_mul_f32_e32 v49, v49, v40
	s_waitcnt vmcnt(6)
	v_mul_f32_e32 v65, v65, v56
	s_waitcnt vmcnt(5)
	v_mul_f32_e32 v81, v81, v72
	s_waitcnt vmcnt(4)
	v_mul_f32_e32 v97, v97, v88
	s_waitcnt vmcnt(3)
	v_mul_f32_e32 v113, v113, v104
	s_waitcnt vmcnt(2)
	v_mul_f32_e32 v129, v129, v120
	s_waitcnt vmcnt(1)
	v_mul_f32_e32 v145, v145, v136
	s_waitcnt vmcnt(0)
	v_mul_f32_e32 v161, v161, v152

; DI u32x4 cvt8(f32x4 a, f32x4 b) { u32x4 r; r.x = pack2(a.x, a.y); r.y = pack2(a.z, a.w); r.z = pack2(b.x, b.y); r.w = pack2(b.z, b.w); return r; }
; DI void prep_transpose(const float* W, int K, int Nsrc, int Nd, int kind, const float* kscale, bf16_t* dst, float* tileL, int L, int G) {
;     ...
;       tileL[kk * 65 + tx] = v;
;     }
;     __syncthreads();
; DI void phase_prep(const Params& P, unsigned char* smem, int L, int G) {
;     ...
;     for (size_t idx = (size_t)L * NTHR + tid; idx < nx8 + np8; idx += (size_t)G * NTHR) {
;       const bool isx = idx < nx8;
;       const size_t e = (isx ? idx : idx - nx8) * 8;
;       const float* src = (isx ? P.x : P.p) + e;
;       const f32x4 f0 = ldgf4(src), f1 = ldgf4(src + 4);
;       *(u32x4*)((isx ? xbw : pbw) + e) = cvt8(f0, f1);
;     }
.Lmy_tp5_w:
	s_waitcnt vmcnt(7)
	ds_write_b32 v2, v49
	s_waitcnt vmcnt(6)
	ds_write_b32 v2, v65 offset:2080
	s_waitcnt vmcnt(5)
	ds_write_b32 v2, v81 offset:4160
	s_waitcnt vmcnt(4)
	ds_write_b32 v2, v97 offset:6240
	s_waitcnt vmcnt(3)
	ds_write_b32 v2, v113 offset:8320
	s_waitcnt vmcnt(2)
	ds_write_b32 v2, v129 offset:10400
	s_waitcnt vmcnt(1)
	ds_write_b32 v2, v145 offset:12480
	s_waitcnt vmcnt(0)
	ds_write_b32 v2, v161 offset:14560
	s_mov_b64 s[98:99], exec
	s_mov_b64 s[100:101], vcc
	s_mov_b64 exec, -1
	v_cmp_gt_u32_e32 vcc, 0x1000000, v236
	s_nop 1
	s_and_b64 exec, exec, vcc
	s_cbranch_execz .Lmy_cvB5
	s_waitcnt vmcnt(0)
	v_cvt_pk_bf16_f32 v170, v170, v171
	v_cvt_pk_bf16_f32 v171, v172, v173
	v_cvt_pk_bf16_f32 v172, v174, v175
	v_cvt_pk_bf16_f32 v173, v176, v177
	global_store_dwordx4 v[178:179], v[170:173], off
	v_cvt_pk_bf16_f32 v180, v180, v181
	v_cvt_pk_bf16_f32 v181, v182, v183
	v_cvt_pk_bf16_f32 v182, v184, v185
	v_cvt_pk_bf16_f32 v183, v186, v187
	global_store_dwordx4 v[188:189], v[180:183], off
	v_cvt_pk_bf16_f32 v194, v194, v195
	v_cvt_pk_bf16_f32 v195, v196, v197
	v_cvt_pk_bf16_f32 v196, v198, v199
	v_cvt_pk_bf16_f32 v197, v200, v201
	global_store_dwordx4 v[202:203], v[194:197], off
	v_cvt_pk_bf16_f32 v204, v204, v205
	v_cvt_pk_bf16_f32 v205, v206, v207
	v_cvt_pk_bf16_f32 v206, v208, v209
	v_cvt_pk_bf16_f32 v207, v210, v211
	global_store_dwordx4 v[212:213], v[204:207], off
	v_cvt_pk_bf16_f32 v214, v214, v215
	v_cvt_pk_bf16_f32 v215, v216, v217
	v_cvt_pk_bf16_f32 v216, v218, v219
	v_cvt_pk_bf16_f32 v217, v220, v221
	global_store_dwordx4 v[222:223], v[214:217], off
	v_lshl_add_u32 v236, s74, 9, v228

; DI void prep_transpose(const float* W, int K, int Nsrc, int Nd, int kind, const float* kscale, bf16_t* dst, float* tileL, int L, int G) {
;     ...
;     __syncthreads();
;     for (int kk = ty; kk < 64; kk += 8) {
;       float v = 0.f;
;       if (src >= 0) { v = W[(size_t)(k0 + kk) * Nsrc + src]; if (kscale) v *= kscale[k0 + kk]; }
;       tileL[kk * 65 + tx] = v;
.Lmy_cvA6:
	s_mov_b64 exec, s[98:99]
	s_mov_b64 vcc, s[100:101]
	v_mov_b32_e32 v40, 0
	v_mov_b32_e32 v56, 0
	v_mov_b32_e32 v72, 0
	v_mov_b32_e32 v88, 0
	v_mov_b32_e32 v104, 0
	v_mov_b32_e32 v120, 0
	v_mov_b32_e32 v136, 0
	v_mov_b32_e32 v152, 0
	s_and_b64 vcc, exec, s[2:3]
	s_cbranch_vccnz .Lmy_tp6_w
	v_add_u32_e32 v40, s23, v13
	v_ashrrev_i32_e32 v41, 31, v40
	v_lshlrev_b64 v[40:41], 10, v[40:41]
	v_lshl_add_u64 v[40:41], v[6:7], 0, v[40:41]
	global_load_dword v40, v[40:41], off
	v_add_u32_e32 v71, 8, v13
	v_add_u32_e32 v56, s23, v71
	v_ashrrev_i32_e32 v57, 31, v56
	v_lshlrev_b64 v[56:57], 10, v[56:57]
	v_lshl_add_u64 v[56:57], v[6:7], 0, v[56:57]
	global_load_dword v56, v[56:57], off
	v_add_u32_e32 v87, 16, v13
	v_add_u32_e32 v72, s23, v87
	v_ashrrev_i32_e32 v73, 31, v72
	v_lshlrev_b64 v[72:73], 10, v[72:73]
	v_lshl_add_u64 v[72:73], v[6:7], 0, v[72:73]
	global_load_dword v72, v[72:73], off
	v_add_u32_e32 v103, 24, v13
	v_add_u32_e32 v88, s23, v103
	v_ashrrev_i32_e32 v89, 31, v88
	v_lshlrev_b64 v[88:89], 10, v[88:89]
	v_lshl_add_u64 v[88:89], v[6:7], 0, v[88:89]
	global_load_dword v88, v[88:89], off
	v_add_u32_e32 v119, 32, v13
	v_add_u32_e32 v104, s23, v119
	v_ashrrev_i32_e32 v105, 31, v104
	v_lshlrev_b64 v[104:105], 10, v[104:105]
	v_lshl_add_u64 v[104:105], v[6:7], 0, v[104:105]
	global_load_dword v104, v[104:105], off
	v_add_u32_e32 v135, 40, v13
	v_add_u32_e32 v120, s23, v135
	v_ashrrev_i32_e32 v121, 31, v120
	v_lshlrev_b64 v[120:121], 10, v[120:121]
	v_lshl_add_u64 v[120:121], v[6:7], 0, v[120:121]
	global_load_dword v120, v[120:121], off
	v_add_u32_e32 v151, 48, v13
	v_add_u32_e32 v136, s23, v151
	v_ashrrev_i32_e32 v137, 31, v136
	v_lshlrev_b64 v[136:137], 10, v[136:137]
	v_lshl_add_u64 v[136:137], v[6:7], 0, v[136:137]
	global_load_dword v136, v[136:137], off
	v_add_u32_e32 v167, 56, v13
	v_add_u32_e32 v152, s23, v167
	v_ashrrev_i32_e32 v153, 31, v152
	v_lshlrev_b64 v[152:153], 10, v[152:153]
	v_lshl_add_u64 v[152:153], v[6:7], 0, v[152:153]
	global_load_dword v152, v[152:153], off

; DI void prep_transpose(const float* W, int K, int Nsrc, int Nd, int kind, const float* kscale, bf16_t* dst, float* tileL, int L, int G) {
;     ...
;     __syncthreads();
;     for (int kk = ty; kk < 64; kk += 8) {
;       float v = 0.f;
;       if (src >= 0) { v = W[(size_t)(k0 + kk) * Nsrc + src]; if (kscale) v *= kscale[k0 + kk]; }
;       tileL[kk * 65 + tx] = v;
.Lmy_cvA8:
	s_mov_b64 exec, s[98:99]
	s_mov_b64 vcc, s[100:101]
	v_mov_b32_e32 v40, 0
	v_mov_b32_e32 v56, 0
	v_mov_b32_e32 v72, 0
	v_mov_b32_e32 v88, 0
	v_mov_b32_e32 v104, 0
	v_mov_b32_e32 v120, 0
	v_mov_b32_e32 v136, 0
	v_mov_b32_e32 v152, 0
	s_and_saveexec_b64 s[2:3], s[0:1]
	s_cbranch_execz .Lmy_tp8_r
	v_add_u32_e32 v40, s25, v13
	v_ashrrev_i32_e32 v41, 31, v40
	v_lshlrev_b64 v[40:41], 8, v[40:41]
	v_lshl_add_u64 v[40:41], v[6:7], 0, v[40:41]
	global_load_dword v40, v[40:41], off
	v_add_u32_e32 v71, 8, v13
	v_add_u32_e32 v56, s25, v71
	v_ashrrev_i32_e32 v57, 31, v56
	v_lshlrev_b64 v[56:57], 8, v[56:57]
	v_lshl_add_u64 v[56:57], v[6:7], 0, v[56:57]
	global_load_dword v56, v[56:57], off
	v_add_u32_e32 v87, 16, v13
	v_add_u32_e32 v72, s25, v87
	v_ashrrev_i32_e32 v73, 31, v72
	v_lshlrev_b64 v[72:73], 8, v[72:73]
	v_lshl_add_u64 v[72:73], v[6:7], 0, v[72:73]
	global_load_dword v72, v[72:73], off
	v_add_u32_e32 v103, 24, v13
	v_add_u32_e32 v88, s25, v103
	v_ashrrev_i32_e32 v89, 31, v88
	v_lshlrev_b64 v[88:89], 8, v[88:89]
	v_lshl_add_u64 v[88:89], v[6:7], 0, v[88:89]
	global_load_dword v88, v[88:89], off
	v_add_u32_e32 v119, 32, v13
	v_add_u32_e32 v104, s25, v119
	v_ashrrev_i32_e32 v105, 31, v104
	v_lshlrev_b64 v[104:105], 8, v[104:105]
	v_lshl_add_u64 v[104:105], v[6:7], 0, v[104:105]
	global_load_dword v104, v[104:105], off
	v_add_u32_e32 v135, 40, v13
	v_add_u32_e32 v120, s25, v135
	v_ashrrev_i32_e32 v121, 31, v120
	v_lshlrev_b64 v[120:121], 8, v[120:121]
	v_lshl_add_u64 v[120:121], v[6:7], 0, v[120:121]
	global_load_dword v120, v[120:121], off
	v_add_u32_e32 v151, 48, v13
	v_add_u32_e32 v136, s25, v151
	v_ashrrev_i32_e32 v137, 31, v136
	v_lshlrev_b64 v[136:137], 8, v[136:137]
	v_lshl_add_u64 v[136:137], v[6:7], 0, v[136:137]
	global_load_dword v136, v[136:137], off
	v_add_u32_e32 v167, 56, v13
	v_add_u32_e32 v152, s25, v167
	v_ashrrev_i32_e32 v153, 31, v152
	v_lshlrev_b64 v[152:153], 8, v[152:153]
	v_lshl_add_u64 v[152:153], v[6:7], 0, v[152:153]
	global_load_dword v152, v[152:153], off

; DI void prep_transpose(const float* W, int K, int Nsrc, int Nd, int kind, const float* kscale, bf16_t* dst, float* tileL, int L, int G) {
;     ...
;     __syncthreads();
;     for (int kk = ty; kk < 64; kk += 8) {
;       float v = 0.f;
;       if (src >= 0) { v = W[(size_t)(k0 + kk) * Nsrc + src]; if (kscale) v *= kscale[k0 + kk]; }
;       tileL[kk * 65 + tx] = v;
.Lmy_cvA9:
	s_mov_b64 exec, s[98:99]
	s_mov_b64 vcc, s[100:101]
	v_mov_b32_e32 v40, 0
	v_mov_b32_e32 v56, 0
	v_mov_b32_e32 v72, 0
	v_mov_b32_e32 v88, 0
	v_mov_b32_e32 v104, 0
	v_mov_b32_e32 v120, 0
	v_mov_b32_e32 v136, 0
	v_mov_b32_e32 v152, 0
	s_and_saveexec_b64 s[2:3], s[0:1]
	s_cbranch_execz .Lmy_tp9_r
	v_add_u32_e32 v40, s22, v13
	v_ashrrev_i32_e32 v41, 31, v40
	v_lshlrev_b64 v[40:41], 8, v[40:41]
	v_lshl_add_u64 v[40:41], v[6:7], 0, v[40:41]
	global_load_dword v40, v[40:41], off
	v_add_u32_e32 v71, 8, v13
	v_add_u32_e32 v56, s22, v71
	v_ashrrev_i32_e32 v57, 31, v56
	v_lshlrev_b64 v[56:57], 8, v[56:57]
	v_lshl_add_u64 v[56:57], v[6:7], 0, v[56:57]
	global_load_dword v56, v[56:57], off
	v_add_u32_e32 v87, 16, v13
	v_add_u32_e32 v72, s22, v87
	v_ashrrev_i32_e32 v73, 31, v72
	v_lshlrev_b64 v[72:73], 8, v[72:73]
	v_lshl_add_u64 v[72:73], v[6:7], 0, v[72:73]
	global_load_dword v72, v[72:73], off
	v_add_u32_e32 v103, 24, v13
	v_add_u32_e32 v88, s22, v103
	v_ashrrev_i32_e32 v89, 31, v88
	v_lshlrev_b64 v[88:89], 8, v[88:89]
	v_lshl_add_u64 v[88:89], v[6:7], 0, v[88:89]
	global_load_dword v88, v[88:89], off
	v_add_u32_e32 v119, 32, v13
	v_add_u32_e32 v104, s22, v119
	v_ashrrev_i32_e32 v105, 31, v104
	v_lshlrev_b64 v[104:105], 8, v[104:105]
	v_lshl_add_u64 v[104:105], v[6:7], 0, v[104:105]
	global_load_dword v104, v[104:105], off
	v_add_u32_e32 v135, 40, v13
	v_add_u32_e32 v120, s22, v135
	v_ashrrev_i32_e32 v121, 31, v120
	v_lshlrev_b64 v[120:121], 8, v[120:121]
	v_lshl_add_u64 v[120:121], v[6:7], 0, v[120:121]
	global_load_dword v120, v[120:121], off
	v_add_u32_e32 v151, 48, v13
	v_add_u32_e32 v136, s22, v151
	v_ashrrev_i32_e32 v137, 31, v136
	v_lshlrev_b64 v[136:137], 8, v[136:137]
	v_lshl_add_u64 v[136:137], v[6:7], 0, v[136:137]
	global_load_dword v136, v[136:137], off
	v_add_u32_e32 v167, 56, v13
	v_add_u32_e32 v152, s22, v167
	v_ashrrev_i32_e32 v153, 31, v152
	v_lshlrev_b64 v[152:153], 8, v[152:153]
	v_lshl_add_u64 v[152:153], v[6:7], 0, v[152:153]
	global_load_dword v152, v[152:153], off

; DI void prep_transpose(const float* W, int K, int Nsrc, int Nd, int kind, const float* kscale, bf16_t* dst, float* tileL, int L, int G) {
;     ...
;     __syncthreads();
;     for (int kk = ty; kk < 64; kk += 8) {
;       float v = 0.f;
;       if (src >= 0) { v = W[(size_t)(k0 + kk) * Nsrc + src]; if (kscale) v *= kscale[k0 + kk]; }
;       tileL[kk * 65 + tx] = v;
.Lmy_cvA10:
	s_mov_b64 exec, s[98:99]
	s_mov_b64 vcc, s[100:101]
	v_mov_b32_e32 v40, 0
	v_mov_b32_e32 v56, 0
	v_mov_b32_e32 v72, 0
	v_mov_b32_e32 v88, 0
	v_mov_b32_e32 v104, 0
	v_mov_b32_e32 v120, 0
	v_mov_b32_e32 v136, 0
	v_mov_b32_e32 v152, 0
	s_and_b64 vcc, exec, s[10:11]
	s_cbranch_vccnz .Lmy_tp10_w
	v_add_u32_e32 v40, s48, v13
	v_ashrrev_i32_e32 v41, 31, v40
	v_lshlrev_b64 v[40:41], 12, v[40:41]
	v_lshl_add_u64 v[40:41], v[6:7], 0, v[40:41]
	global_load_dword v40, v[40:41], off
	v_add_u32_e32 v71, 8, v13
	v_add_u32_e32 v56, s48, v71
	v_ashrrev_i32_e32 v57, 31, v56
	v_lshlrev_b64 v[56:57], 12, v[56:57]
	v_lshl_add_u64 v[56:57], v[6:7], 0, v[56:57]
	global_load_dword v56, v[56:57], off
	v_add_u32_e32 v87, 16, v13
	v_add_u32_e32 v72, s48, v87
	v_ashrrev_i32_e32 v73, 31, v72
	v_lshlrev_b64 v[72:73], 12, v[72:73]
	v_lshl_add_u64 v[72:73], v[6:7], 0, v[72:73]
	global_load_dword v72, v[72:73], off
	v_add_u32_e32 v103, 24, v13
	v_add_u32_e32 v88, s48, v103
	v_ashrrev_i32_e32 v89, 31, v88
	v_lshlrev_b64 v[88:89], 12, v[88:89]
	v_lshl_add_u64 v[88:89], v[6:7], 0, v[88:89]
	global_load_dword v88, v[88:89], off
	v_add_u32_e32 v119, 32, v13
	v_add_u32_e32 v104, s48, v119
	v_ashrrev_i32_e32 v105, 31, v104
	v_lshlrev_b64 v[104:105], 12, v[104:105]
	v_lshl_add_u64 v[104:105], v[6:7], 0, v[104:105]
	global_load_dword v104, v[104:105], off
	v_add_u32_e32 v135, 40, v13
	v_add_u32_e32 v120, s48, v135
	v_ashrrev_i32_e32 v121, 31, v120
	v_lshlrev_b64 v[120:121], 12, v[120:121]
	v_lshl_add_u64 v[120:121], v[6:7], 0, v[120:121]
	global_load_dword v120, v[120:121], off
	v_add_u32_e32 v151, 48, v13
	v_add_u32_e32 v136, s48, v151
	v_ashrrev_i32_e32 v137, 31, v136
	v_lshlrev_b64 v[136:137], 12, v[136:137]
	v_lshl_add_u64 v[136:137], v[6:7], 0, v[136:137]
	global_load_dword v136, v[136:137], off
	v_add_u32_e32 v167, 56, v13
	v_add_u32_e32 v152, s48, v167
	v_ashrrev_i32_e32 v153, 31, v152
	v_lshlrev_b64 v[152:153], 12, v[152:153]
	v_lshl_add_u64 v[152:153], v[6:7], 0, v[152:153]
	global_load_dword v152, v[152:153], off

; DI u32x4 cvt8(f32x4 a, f32x4 b) { u32x4 r; r.x = pack2(a.x, a.y); r.y = pack2(a.z, a.w); r.z = pack2(b.x, b.y); r.w = pack2(b.z, b.w); return r; }
; DI void prep_transpose(const float* W, int K, int Nsrc, int Nd, int kind, const float* kscale, bf16_t* dst, float* tileL, int L, int G) {
;     ...
;     __syncthreads();
;     for (int kk = ty; kk < 64; kk += 8) {
;       float v = 0.f;
;       if (src >= 0) { v = W[(size_t)(k0 + kk) * Nsrc + src]; if (kscale) v *= kscale[k0 + kk]; }
;       tileL[kk * 65 + tx] = v;
;     }
;     __syncthreads();
; DI void phase_prep(const Params& P, unsigned char* smem, int L, int G) {
;     ...
;     for (size_t idx = (size_t)L * NTHR + tid; idx < nx8 + np8; idx += (size_t)G * NTHR) {
;       const bool isx = idx < nx8;
;       const size_t e = (isx ? idx : idx - nx8) * 8;
;       const float* src = (isx ? P.x : P.p) + e;
;       const f32x4 f0 = ldgf4(src), f1 = ldgf4(src + 4);
;       *(u32x4*)((isx ? xbw : pbw) + e) = cvt8(f0, f1);
;     }
.Lmy_cvA11:
	s_mov_b64 exec, s[98:99]
	s_mov_b64 vcc, s[100:101]
	v_mov_b32_e32 v48, 0
	v_mov_b32_e32 v64, 0
	v_mov_b32_e32 v80, 0
	v_mov_b32_e32 v96, 0
	v_mov_b32_e32 v112, 0
	v_mov_b32_e32 v128, 0
	v_mov_b32_e32 v144, 0
	v_mov_b32_e32 v160, 0
	s_and_b64 vcc, exec, s[10:11]
	s_cbranch_vccnz .Lmy_tp11_w
	v_add_u32_e32 v40, s50, v15
	v_ashrrev_i32_e32 v41, 31, v40
	v_lshlrev_b64 v[48:49], 12, v[40:41]
	v_lshl_add_u64 v[48:49], v[6:7], 0, v[48:49]
	global_load_dword v48, v[48:49], off
	v_add_u32_e32 v71, 8, v15
	v_add_u32_e32 v56, s50, v71
	v_ashrrev_i32_e32 v57, 31, v56
	v_lshlrev_b64 v[64:65], 12, v[56:57]
	v_lshl_add_u64 v[64:65], v[6:7], 0, v[64:65]
	global_load_dword v64, v[64:65], off
	v_add_u32_e32 v87, 16, v15
	v_add_u32_e32 v72, s50, v87
	v_ashrrev_i32_e32 v73, 31, v72
	v_lshlrev_b64 v[80:81], 12, v[72:73]
	v_lshl_add_u64 v[80:81], v[6:7], 0, v[80:81]
	global_load_dword v80, v[80:81], off
	v_add_u32_e32 v103, 24, v15
	v_add_u32_e32 v88, s50, v103
	v_ashrrev_i32_e32 v89, 31, v88
	v_lshlrev_b64 v[96:97], 12, v[88:89]
	v_lshl_add_u64 v[96:97], v[6:7], 0, v[96:97]
	global_load_dword v96, v[96:97], off
	v_add_u32_e32 v119, 32, v15
	v_add_u32_e32 v104, s50, v119
	v_ashrrev_i32_e32 v105, 31, v104
	v_lshlrev_b64 v[112:113], 12, v[104:105]
	v_lshl_add_u64 v[112:113], v[6:7], 0, v[112:113]
	global_load_dword v112, v[112:113], off
	v_add_u32_e32 v135, 40, v15
	v_add_u32_e32 v120, s50, v135
	v_ashrrev_i32_e32 v121, 31, v120
	v_lshlrev_b64 v[128:129], 12, v[120:121]
	v_lshl_add_u64 v[128:129], v[6:7], 0, v[128:129]
	global_load_dword v128, v[128:129], off
	v_add_u32_e32 v151, 48, v15
	v_add_u32_e32 v136, s50, v151
	v_ashrrev_i32_e32 v137, 31, v136
	v_lshlrev_b64 v[144:145], 12, v[136:137]
	v_lshl_add_u64 v[144:145], v[6:7], 0, v[144:145]
	global_load_dword v144, v[144:145], off
	v_add_u32_e32 v167, 56, v15
	v_add_u32_e32 v152, s50, v167
	v_ashrrev_i32_e32 v153, 31, v152
	v_lshlrev_b64 v[160:161], 12, v[152:153]
	v_lshl_add_u64 v[160:161], v[6:7], 0, v[160:161]
	global_load_dword v160, v[160:161], off
	s_and_b64 vcc, exec, s[2:3]
	s_cbranch_vccnz .Lmy_tp11_r
	v_lshl_add_u64 v[40:41], v[40:41], 2, s[38:39]
	global_load_dword v40, v[40:41], off
	v_lshl_add_u64 v[56:57], v[56:57], 2, s[38:39]
	global_load_dword v56, v[56:57], off
	v_lshl_add_u64 v[72:73], v[72:73], 2, s[38:39]
	global_load_dword v72, v[72:73], off
	v_lshl_add_u64 v[88:89], v[88:89], 2, s[38:39]
	global_load_dword v88, v[88:89], off
	v_lshl_add_u64 v[104:105], v[104:105], 2, s[38:39]
	global_load_dword v104, v[104:105], off
	v_lshl_add_u64 v[120:121], v[120:121], 2, s[38:39]
	global_load_dword v120, v[120:121], off
	v_lshl_add_u64 v[136:137], v[136:137], 2, s[38:39]
	global_load_dword v136, v[136:137], off
	v_lshl_add_u64 v[152:153], v[152:153], 2, s[38:39]
	global_load_dword v152, v[152:153], off
	s_waitcnt vmcnt(7)
	v_mul_f32_e32 v48, v48, v40
	s_waitcnt vmcnt(6)
	v_mul_f32_e32 v64, v64, v56
	s_waitcnt vmcnt(5)
	v_mul_f32_e32 v80, v80, v72
	s_waitcnt vmcnt(4)
	v_mul_f32_e32 v96, v96, v88
	s_waitcnt vmcnt(3)
	v_mul_f32_e32 v112, v112, v104
	s_waitcnt vmcnt(2)
	v_mul_f32_e32 v128, v128, v120
	s_waitcnt vmcnt(1)
	v_mul_f32_e32 v144, v144, v136
	s_waitcnt vmcnt(0)
	v_mul_f32_e32 v160, v160, v152
.Lmy_tp11_r:
.Lmy_tp11_w:
	s_waitcnt vmcnt(7)
	ds_write_b32 v2, v48
	s_waitcnt vmcnt(6)
	ds_write_b32 v2, v64 offset:2080
	s_waitcnt vmcnt(5)
	ds_write_b32 v2, v80 offset:4160
	s_waitcnt vmcnt(4)
	ds_write_b32 v2, v96 offset:6240
	s_waitcnt vmcnt(3)
	ds_write_b32 v2, v112 offset:8320
	s_waitcnt vmcnt(2)
	ds_write_b32 v2, v128 offset:10400
	s_waitcnt vmcnt(1)
	ds_write_b32 v2, v144 offset:12480
	s_waitcnt vmcnt(0)
	ds_write_b32 v2, v160 offset:14560
	s_mov_b64 s[98:99], exec
	s_mov_b64 s[100:101], vcc
	s_mov_b64 exec, -1
	v_cmp_gt_u32_e32 vcc, 0x1000000, v236
	s_nop 1
	s_and_b64 exec, exec, vcc
	s_cbranch_execz .Lmy_cvB11
	s_waitcnt vmcnt(0)
	v_cvt_pk_bf16_f32 v170, v170, v171
	v_cvt_pk_bf16_f32 v171, v172, v173
	v_cvt_pk_bf16_f32 v172, v174, v175
	v_cvt_pk_bf16_f32 v173, v176, v177
	global_store_dwordx4 v[178:179], v[170:173], off
	v_cvt_pk_bf16_f32 v180, v180, v181
	v_cvt_pk_bf16_f32 v181, v182, v183
	v_cvt_pk_bf16_f32 v182, v184, v185
	v_cvt_pk_bf16_f32 v183, v186, v187
	global_store_dwordx4 v[188:189], v[180:183], off
	v_cvt_pk_bf16_f32 v194, v194, v195
	v_cvt_pk_bf16_f32 v195, v196, v197
	v_cvt_pk_bf16_f32 v196, v198, v199
	v_cvt_pk_bf16_f32 v197, v200, v201
	global_store_dwordx4 v[202:203], v[194:197], off
	v_cvt_pk_bf16_f32 v204, v204, v205
	v_cvt_pk_bf16_f32 v205, v206, v207
	v_cvt_pk_bf16_f32 v206, v208, v209
	v_cvt_pk_bf16_f32 v207, v210, v211
	global_store_dwordx4 v[212:213], v[204:207], off
	v_cvt_pk_bf16_f32 v214, v214, v215
	v_cvt_pk_bf16_f32 v215, v216, v217
	v_cvt_pk_bf16_f32 v216, v218, v219
	v_cvt_pk_bf16_f32 v217, v220, v221
	global_store_dwordx4 v[222:223], v[214:217], off
	v_lshl_add_u32 v236, s74, 9, v228

; DI void prep_transpose(const float* W, int K, int Nsrc, int Nd, int kind, const float* kscale, bf16_t* dst, float* tileL, int L, int G) {
;     ...
;     __syncthreads();
;     for (int kk = ty; kk < 64; kk += 8) {
;       float v = 0.f;
;       if (src >= 0) { v = W[(size_t)(k0 + kk) * Nsrc + src]; if (kscale) v *= kscale[k0 + kk]; }
;       tileL[kk * 65 + tx] = v;
.Lmy_cvA12:
	s_mov_b64 exec, s[98:99]
	s_mov_b64 vcc, s[100:101]
	v_mov_b32_e32 v40, 0
	v_mov_b32_e32 v56, 0
	v_mov_b32_e32 v72, 0
	v_mov_b32_e32 v88, 0
	v_mov_b32_e32 v104, 0
	v_mov_b32_e32 v120, 0
	v_mov_b32_e32 v136, 0
	v_mov_b32_e32 v152, 0
	s_andn2_b64 vcc, exec, s[38:39]
	s_cbranch_vccnz .Lmy_tp12_w
	v_add_u32_e32 v40, s46, v13
	v_ashrrev_i32_e32 v41, 31, v40
	v_lshlrev_b64 v[40:41], 12, v[40:41]
	v_lshl_add_u64 v[40:41], v[6:7], 0, v[40:41]
	global_load_dword v40, v[40:41], off
	v_add_u32_e32 v71, 8, v13
	v_add_u32_e32 v56, s46, v71
	v_ashrrev_i32_e32 v57, 31, v56
	v_lshlrev_b64 v[56:57], 12, v[56:57]
	v_lshl_add_u64 v[56:57], v[6:7], 0, v[56:57]
	global_load_dword v56, v[56:57], off
	v_add_u32_e32 v87, 16, v13
	v_add_u32_e32 v72, s46, v87
	v_ashrrev_i32_e32 v73, 31, v72
	v_lshlrev_b64 v[72:73], 12, v[72:73]
	v_lshl_add_u64 v[72:73], v[6:7], 0, v[72:73]
	global_load_dword v72, v[72:73], off
	v_add_u32_e32 v103, 24, v13
	v_add_u32_e32 v88, s46, v103
	v_ashrrev_i32_e32 v89, 31, v88
	v_lshlrev_b64 v[88:89], 12, v[88:89]
	v_lshl_add_u64 v[88:89], v[6:7], 0, v[88:89]
	global_load_dword v88, v[88:89], off
	v_add_u32_e32 v119, 32, v13
	v_add_u32_e32 v104, s46, v119
	v_ashrrev_i32_e32 v105, 31, v104
	v_lshlrev_b64 v[104:105], 12, v[104:105]
	v_lshl_add_u64 v[104:105], v[6:7], 0, v[104:105]
	global_load_dword v104, v[104:105], off
	v_add_u32_e32 v135, 40, v13
	v_add_u32_e32 v120, s46, v135
	v_ashrrev_i32_e32 v121, 31, v120
	v_lshlrev_b64 v[120:121], 12, v[120:121]
	v_lshl_add_u64 v[120:121], v[6:7], 0, v[120:121]
	global_load_dword v120, v[120:121], off
	v_add_u32_e32 v151, 48, v13
	v_add_u32_e32 v136, s46, v151
	v_ashrrev_i32_e32 v137, 31, v136
	v_lshlrev_b64 v[136:137], 12, v[136:137]
	v_lshl_add_u64 v[136:137], v[6:7], 0, v[136:137]
	global_load_dword v136, v[136:137], off
	v_add_u32_e32 v167, 56, v13
	v_add_u32_e32 v152, s46, v167
	v_ashrrev_i32_e32 v153, 31, v152
	v_lshlrev_b64 v[152:153], 12, v[152:153]
	v_lshl_add_u64 v[152:153], v[6:7], 0, v[152:153]
	global_load_dword v152, v[152:153], off

; DI u32x4 cvt8(f32x4 a, f32x4 b) { u32x4 r; r.x = pack2(a.x, a.y); r.y = pack2(a.z, a.w); r.z = pack2(b.x, b.y); r.w = pack2(b.z, b.w); return r; }
; DI void phase_prep(const Params& P, unsigned char* smem, int L, int G) {
;     ...
;     bf16_t* xbw = (bf16_t*)(ws + OFF_XB); bf16_t* pbw = (bf16_t*)(ws + OFF_PB);
;     const size_t nx8 = (size_t)MTOK * 1024 / 8, np8 = (size_t)4 * MTOK * 256 / 8;
;     for (size_t idx = (size_t)L * NTHR + tid; idx < nx8 + np8; idx += (size_t)G * NTHR) {
;       const bool isx = idx < nx8;
;       const size_t e = (isx ? idx : idx - nx8) * 8;
;       const float* src = (isx ? P.x : P.p) + e;
;       const f32x4 f0 = ldgf4(src), f1 = ldgf4(src + 4);
;       *(u32x4*)((isx ? xbw : pbw) + e) = cvt8(f0, f1);
;     }
.LBB0_167:
	s_ashr_i32 s71, s70, 31
	s_lshl_b64 s[0:1], s[70:71], 9
	v_ashrrev_i32_e32 v1, 31, v0
	v_lshl_add_u64 v[2:3], s[0:1], 0, v[0:1]
	s_mov_b64 s[0:1], 0x1000000
	v_cmp_gt_u32_e32 vcc, 0x1000000, v236
	v_writelane_b32 v246, s52, 22
	s_and_saveexec_b64 s[0:1], vcc
	s_cbranch_execz .LBB0_170
	v_readlane_b32 s40, v246, 1
	s_ashr_i32 s5, s74, 31
	s_mov_b32 s4, s74
	s_lshl_b64 s[30:31], s[70:71], 12
	s_brev_b32 s36, 63
	v_readlane_b32 s41, v246, 2
	v_readlane_b32 s42, v246, 3
	v_readlane_b32 s43, v246, 4
	s_lshl_b64 s[2:3], s[4:5], 9
	v_lshlrev_b32_e32 v4, 3, v236
	v_mov_b32_e32 v5, 0
	s_lshl_b64 s[4:5], s[4:5], 12
	s_mov_b64 s[30:31], 0
	s_mov_b64 s[34:35], 0x800000
	s_mov_b32 s37, -1
	v_mov_b32_e32 v1, 0x3637c800
	v_mov_b32_e32 v10, 0x4f68800
	v_mov_b32_e32 v7, 0
	v_mov_b32_e32 v11, s43
	v_mov_b32_e32 v12, s41
	v_mov_b32_e32 v13, s42
	v_mov_b32_e32 v14, s40
	s_mov_b64 s[38:39], 0xffffff
	v_mov_b32_e32 v8, v236
	v_mov_b32_e32 v9, 0
	v_readlane_b32 s44, v246, 5
	v_readlane_b32 s45, v246, 6
	v_readlane_b32 s46, v246, 7
	v_readlane_b32 s47, v246, 8
	v_readlane_b32 s48, v246, 9
	v_readlane_b32 s49, v246, 10
	v_readlane_b32 s50, v246, 11
	v_readlane_b32 s51, v246, 12
	v_readlane_b32 s52, v246, 13
	v_readlane_b32 s53, v246, 14
	v_readlane_b32 s54, v246, 15
	v_readlane_b32 s55, v246, 16
